# previous plus P5 meta-row thin GEMM: 4 k-blocks per trip with 32 loads in flight
# speedup vs baseline: 1.0040x; 1.0034x over previous
.Lthin_p50_g:
	s_add_i32 s100, s7, 4
	s_cmp_gt_i32 s100, s26
	s_cbranch_scc1 .Lthin_p50_t
	s_mov_b32 s98, s22
	s_ashr_i32 s99, s22, 31
	s_lshl_b64 s[98:99], s[98:99], 1
	v_lshl_add_u64 v[186:187], v[6:7], 0, s[98:99]
	v_lshl_add_u64 v[240:241], v[12:13], 0, s[98:99]
	global_load_dwordx4 v[56:59], v[186:187], off
	global_load_dwordx4 v[60:63], v[240:241], off
	global_load_dwordx4 v[64:67], v[186:187], off offset:16
	global_load_dwordx4 v[68:71], v[240:241], off offset:16
	global_load_dwordx4 v[72:75], v[186:187], off offset:32
	global_load_dwordx4 v[76:79], v[240:241], off offset:32
	global_load_dwordx4 v[80:83], v[186:187], off offset:48
	global_load_dwordx4 v[84:87], v[240:241], off offset:48
	global_load_dwordx4 v[88:91], v[186:187], off offset:256
	global_load_dwordx4 v[92:95], v[240:241], off offset:256
	global_load_dwordx4 v[96:99], v[186:187], off offset:272
	global_load_dwordx4 v[100:103], v[240:241], off offset:272
	global_load_dwordx4 v[104:107], v[186:187], off offset:288
	global_load_dwordx4 v[108:111], v[240:241], off offset:288
	global_load_dwordx4 v[112:115], v[186:187], off offset:304
	global_load_dwordx4 v[116:119], v[240:241], off offset:304
	global_load_dwordx4 v[120:123], v[186:187], off offset:512
	global_load_dwordx4 v[124:127], v[240:241], off offset:512
	global_load_dwordx4 v[128:131], v[186:187], off offset:528
	global_load_dwordx4 v[132:135], v[240:241], off offset:528
	global_load_dwordx4 v[136:139], v[186:187], off offset:544
	global_load_dwordx4 v[140:143], v[240:241], off offset:544
	global_load_dwordx4 v[144:147], v[186:187], off offset:560
	global_load_dwordx4 v[148:151], v[240:241], off offset:560
	global_load_dwordx4 v[152:155], v[186:187], off offset:768
	global_load_dwordx4 v[156:159], v[240:241], off offset:768
	global_load_dwordx4 v[160:163], v[186:187], off offset:784
	global_load_dwordx4 v[164:167], v[240:241], off offset:784
	global_load_dwordx4 v[168:171], v[186:187], off offset:800
	global_load_dwordx4 v[172:175], v[240:241], off offset:800
	global_load_dwordx4 v[176:179], v[186:187], off offset:816
	global_load_dwordx4 v[188:191], v[240:241], off offset:816
	s_add_i32 s7, s7, 4
	s_addk_i32 s22, 0x200
	s_waitcnt vmcnt(30)
	v_mfma_f32_16x16x32_bf16 v[2:5], v[56:59], v[60:63], v[2:5]
	s_waitcnt vmcnt(28)
	v_mfma_f32_16x16x32_bf16 v[2:5], v[64:67], v[68:71], v[2:5]
	s_waitcnt vmcnt(26)
	v_mfma_f32_16x16x32_bf16 v[2:5], v[72:75], v[76:79], v[2:5]
	s_waitcnt vmcnt(24)
	v_mfma_f32_16x16x32_bf16 v[2:5], v[80:83], v[84:87], v[2:5]
	s_waitcnt vmcnt(22)
	v_mfma_f32_16x16x32_bf16 v[2:5], v[88:91], v[92:95], v[2:5]
	s_waitcnt vmcnt(20)
	v_mfma_f32_16x16x32_bf16 v[2:5], v[96:99], v[100:103], v[2:5]
	s_waitcnt vmcnt(18)
	v_mfma_f32_16x16x32_bf16 v[2:5], v[104:107], v[108:111], v[2:5]
	s_waitcnt vmcnt(16)
	v_mfma_f32_16x16x32_bf16 v[2:5], v[112:115], v[116:119], v[2:5]
	s_waitcnt vmcnt(14)
	v_mfma_f32_16x16x32_bf16 v[2:5], v[120:123], v[124:127], v[2:5]
	s_waitcnt vmcnt(12)
	v_mfma_f32_16x16x32_bf16 v[2:5], v[128:131], v[132:135], v[2:5]
	s_waitcnt vmcnt(10)
	v_mfma_f32_16x16x32_bf16 v[2:5], v[136:139], v[140:143], v[2:5]
	s_waitcnt vmcnt(8)
	v_mfma_f32_16x16x32_bf16 v[2:5], v[144:147], v[148:151], v[2:5]
	s_waitcnt vmcnt(6)
	v_mfma_f32_16x16x32_bf16 v[2:5], v[152:155], v[156:159], v[2:5]
	s_waitcnt vmcnt(4)
	v_mfma_f32_16x16x32_bf16 v[2:5], v[160:163], v[164:167], v[2:5]
	s_waitcnt vmcnt(2)
	v_mfma_f32_16x16x32_bf16 v[2:5], v[168:171], v[172:175], v[2:5]
	s_waitcnt vmcnt(0)
	v_mfma_f32_16x16x32_bf16 v[2:5], v[176:179], v[188:191], v[2:5]
	s_branch .Lthin_p50_g
.Lthin_p50_t:
	s_cmp_ge_i32 s7, s26
	s_cbranch_scc1 .LBB0_2073
.LBB0_2072:
	s_ashr_i32 s23, s22, 31
	s_lshl_b64 s[24:25], s[22:23], 1
	v_lshl_add_u64 v[50:51], v[6:7], 0, s[24:25]
	v_lshl_add_u64 v[52:53], v[12:13], 0, s[24:25]
	global_load_dwordx4 v[18:21], v[50:51], off
	global_load_dwordx4 v[22:25], v[50:51], off offset:16
	global_load_dwordx4 v[26:29], v[52:53], off
	global_load_dwordx4 v[30:33], v[50:51], off offset:32
	global_load_dwordx4 v[34:37], v[52:53], off offset:16
	global_load_dwordx4 v[38:41], v[52:53], off offset:32
	global_load_dwordx4 v[42:45], v[50:51], off offset:48
	global_load_dwordx4 v[46:49], v[52:53], off offset:48
	s_add_i32 s7, s7, 2
	s_addk_i32 s22, 0x100
	s_cmp_ge_i32 s7, s26
	s_waitcnt vmcnt(5)
	v_mfma_f32_16x16x32_bf16 v[2:5], v[18:21], v[26:29], v[2:5]
	global_load_dwordx4 v[18:21], v[50:51], off offset:256
	global_load_dwordx4 v[26:29], v[50:51], off offset:272
	s_waitcnt vmcnt(5)
	v_mfma_f32_16x16x32_bf16 v[2:5], v[22:25], v[34:37], v[2:5]
	global_load_dwordx4 v[22:25], v[52:53], off offset:256
	s_waitcnt vmcnt(5)
	v_mfma_f32_16x16x32_bf16 v[2:5], v[30:33], v[38:41], v[2:5]
	global_load_dwordx4 v[30:33], v[52:53], off offset:272
	global_load_dwordx4 v[34:37], v[50:51], off offset:288
	global_load_dwordx4 v[38:41], v[50:51], off offset:304
	s_waitcnt vmcnt(6)
	v_mfma_f32_16x16x32_bf16 v[2:5], v[42:45], v[46:49], v[2:5]
	s_waitcnt vmcnt(3)
	v_mfma_f32_16x16x32_bf16 v[2:5], v[18:21], v[22:25], v[2:5]
	global_load_dwordx4 v[18:21], v[52:53], off offset:288
	global_load_dwordx4 v[22:25], v[52:53], off offset:304
	s_waitcnt vmcnt(4)
	v_mfma_f32_16x16x32_bf16 v[2:5], v[26:29], v[30:33], v[2:5]
	s_waitcnt vmcnt(1)
	v_mfma_f32_16x16x32_bf16 v[2:5], v[34:37], v[18:21], v[2:5]
	s_waitcnt vmcnt(0)
	v_mfma_f32_16x16x32_bf16 v[2:5], v[38:41], v[22:25], v[2:5]
	s_cbranch_scc0 .LBB0_2072

.Lthin_p51_g:
	s_add_i32 s100, s7, 4
	s_cmp_gt_i32 s100, s26
	s_cbranch_scc1 .Lthin_p51_t
	s_mov_b32 s98, s24
	s_ashr_i32 s99, s24, 31
	s_lshl_b64 s[98:99], s[98:99], 1
	v_lshl_add_u64 v[186:187], v[6:7], 0, s[98:99]
	v_lshl_add_u64 v[240:241], v[12:13], 0, s[98:99]
	global_load_dwordx4 v[56:59], v[186:187], off
	global_load_dwordx4 v[60:63], v[240:241], off
	global_load_dwordx4 v[64:67], v[186:187], off offset:16
	global_load_dwordx4 v[68:71], v[240:241], off offset:16
	global_load_dwordx4 v[72:75], v[186:187], off offset:32
	global_load_dwordx4 v[76:79], v[240:241], off offset:32
	global_load_dwordx4 v[80:83], v[186:187], off offset:48
	global_load_dwordx4 v[84:87], v[240:241], off offset:48
	global_load_dwordx4 v[88:91], v[186:187], off offset:256
	global_load_dwordx4 v[92:95], v[240:241], off offset:256
	global_load_dwordx4 v[96:99], v[186:187], off offset:272
	global_load_dwordx4 v[100:103], v[240:241], off offset:272
	global_load_dwordx4 v[104:107], v[186:187], off offset:288
	global_load_dwordx4 v[108:111], v[240:241], off offset:288
	global_load_dwordx4 v[112:115], v[186:187], off offset:304
	global_load_dwordx4 v[116:119], v[240:241], off offset:304
	global_load_dwordx4 v[120:123], v[186:187], off offset:512
	global_load_dwordx4 v[124:127], v[240:241], off offset:512
	global_load_dwordx4 v[128:131], v[186:187], off offset:528
	global_load_dwordx4 v[132:135], v[240:241], off offset:528
	global_load_dwordx4 v[136:139], v[186:187], off offset:544
	global_load_dwordx4 v[140:143], v[240:241], off offset:544
	global_load_dwordx4 v[144:147], v[186:187], off offset:560
	global_load_dwordx4 v[148:151], v[240:241], off offset:560
	global_load_dwordx4 v[152:155], v[186:187], off offset:768
	global_load_dwordx4 v[156:159], v[240:241], off offset:768
	global_load_dwordx4 v[160:163], v[186:187], off offset:784
	global_load_dwordx4 v[164:167], v[240:241], off offset:784
	global_load_dwordx4 v[168:171], v[186:187], off offset:800
	global_load_dwordx4 v[172:175], v[240:241], off offset:800
	global_load_dwordx4 v[176:179], v[186:187], off offset:816
	global_load_dwordx4 v[188:191], v[240:241], off offset:816
	s_add_i32 s7, s7, 4
	s_addk_i32 s24, 0x200
	s_waitcnt vmcnt(30)
	v_mfma_f32_16x16x32_bf16 v[2:5], v[56:59], v[60:63], v[2:5]
	s_waitcnt vmcnt(28)
	v_mfma_f32_16x16x32_bf16 v[2:5], v[64:67], v[68:71], v[2:5]
	s_waitcnt vmcnt(26)
	v_mfma_f32_16x16x32_bf16 v[2:5], v[72:75], v[76:79], v[2:5]
	s_waitcnt vmcnt(24)
	v_mfma_f32_16x16x32_bf16 v[2:5], v[80:83], v[84:87], v[2:5]
	s_waitcnt vmcnt(22)
	v_mfma_f32_16x16x32_bf16 v[2:5], v[88:91], v[92:95], v[2:5]
	s_waitcnt vmcnt(20)
	v_mfma_f32_16x16x32_bf16 v[2:5], v[96:99], v[100:103], v[2:5]
	s_waitcnt vmcnt(18)
	v_mfma_f32_16x16x32_bf16 v[2:5], v[104:107], v[108:111], v[2:5]
	s_waitcnt vmcnt(16)
	v_mfma_f32_16x16x32_bf16 v[2:5], v[112:115], v[116:119], v[2:5]
	s_waitcnt vmcnt(14)
	v_mfma_f32_16x16x32_bf16 v[2:5], v[120:123], v[124:127], v[2:5]
	s_waitcnt vmcnt(12)
	v_mfma_f32_16x16x32_bf16 v[2:5], v[128:131], v[132:135], v[2:5]
	s_waitcnt vmcnt(10)
	v_mfma_f32_16x16x32_bf16 v[2:5], v[136:139], v[140:143], v[2:5]
	s_waitcnt vmcnt(8)
	v_mfma_f32_16x16x32_bf16 v[2:5], v[144:147], v[148:151], v[2:5]
	s_waitcnt vmcnt(6)
	v_mfma_f32_16x16x32_bf16 v[2:5], v[152:155], v[156:159], v[2:5]
	s_waitcnt vmcnt(4)
	v_mfma_f32_16x16x32_bf16 v[2:5], v[160:163], v[164:167], v[2:5]
	s_waitcnt vmcnt(2)
	v_mfma_f32_16x16x32_bf16 v[2:5], v[168:171], v[172:175], v[2:5]
	s_waitcnt vmcnt(0)
	v_mfma_f32_16x16x32_bf16 v[2:5], v[176:179], v[188:191], v[2:5]
	s_branch .Lthin_p51_g
.Lthin_p51_t:
	s_cmp_ge_i32 s7, s26
	s_cbranch_scc1 .LBB0_2078
.LBB0_2077:
	s_ashr_i32 s25, s24, 31
	s_lshl_b64 s[40:41], s[24:25], 1
	v_lshl_add_u64 v[50:51], v[6:7], 0, s[40:41]
	v_lshl_add_u64 v[52:53], v[12:13], 0, s[40:41]
	global_load_dwordx4 v[18:21], v[50:51], off
	global_load_dwordx4 v[22:25], v[50:51], off offset:16
	global_load_dwordx4 v[26:29], v[52:53], off
	global_load_dwordx4 v[30:33], v[50:51], off offset:32
	global_load_dwordx4 v[34:37], v[52:53], off offset:16
	global_load_dwordx4 v[38:41], v[52:53], off offset:32
	global_load_dwordx4 v[42:45], v[50:51], off offset:48
	global_load_dwordx4 v[46:49], v[52:53], off offset:48
	s_add_i32 s7, s7, 2
	s_addk_i32 s24, 0x100
	s_cmp_lt_i32 s7, s26
	s_waitcnt vmcnt(5)
	v_mfma_f32_16x16x32_bf16 v[2:5], v[18:21], v[26:29], v[2:5]
	global_load_dwordx4 v[18:21], v[50:51], off offset:256
	global_load_dwordx4 v[26:29], v[50:51], off offset:272
	s_waitcnt vmcnt(5)
	v_mfma_f32_16x16x32_bf16 v[2:5], v[22:25], v[34:37], v[2:5]
	global_load_dwordx4 v[22:25], v[52:53], off offset:256
	s_waitcnt vmcnt(5)
	v_mfma_f32_16x16x32_bf16 v[2:5], v[30:33], v[38:41], v[2:5]
	global_load_dwordx4 v[30:33], v[52:53], off offset:272
	global_load_dwordx4 v[34:37], v[50:51], off offset:288
	global_load_dwordx4 v[38:41], v[50:51], off offset:304
	s_waitcnt vmcnt(6)
	v_mfma_f32_16x16x32_bf16 v[2:5], v[42:45], v[46:49], v[2:5]
	s_waitcnt vmcnt(3)
	v_mfma_f32_16x16x32_bf16 v[2:5], v[18:21], v[22:25], v[2:5]
	global_load_dwordx4 v[18:21], v[52:53], off offset:288
	global_load_dwordx4 v[22:25], v[52:53], off offset:304
	s_waitcnt vmcnt(4)
	v_mfma_f32_16x16x32_bf16 v[2:5], v[26:29], v[30:33], v[2:5]
	s_waitcnt vmcnt(1)
	v_mfma_f32_16x16x32_bf16 v[2:5], v[34:37], v[18:21], v[2:5]
	s_waitcnt vmcnt(0)
	v_mfma_f32_16x16x32_bf16 v[2:5], v[38:41], v[22:25], v[2:5]
	s_cbranch_scc1 .LBB0_2077

.Lthin_p52_t:
	s_cmp_ge_i32 s7, s26
	s_cbranch_scc1 .LBB0_2083
.LBB0_2082:
	s_ashr_i32 s25, s24, 31
	s_lshl_b64 s[40:41], s[24:25], 1
	v_lshl_add_u64 v[50:51], v[6:7], 0, s[40:41]
	v_lshl_add_u64 v[52:53], v[12:13], 0, s[40:41]
	global_load_dwordx4 v[18:21], v[50:51], off
	global_load_dwordx4 v[22:25], v[50:51], off offset:16
	global_load_dwordx4 v[26:29], v[52:53], off
	global_load_dwordx4 v[30:33], v[50:51], off offset:32
	global_load_dwordx4 v[34:37], v[52:53], off offset:16
	global_load_dwordx4 v[38:41], v[52:53], off offset:32
	global_load_dwordx4 v[42:45], v[50:51], off offset:48
	global_load_dwordx4 v[46:49], v[52:53], off offset:48
	s_add_i32 s7, s7, 2
	s_addk_i32 s24, 0x100
	s_cmp_lt_i32 s7, s26
	s_waitcnt vmcnt(5)
	v_mfma_f32_16x16x32_bf16 v[2:5], v[18:21], v[26:29], v[2:5]
	global_load_dwordx4 v[18:21], v[50:51], off offset:256
	global_load_dwordx4 v[26:29], v[50:51], off offset:272
	s_waitcnt vmcnt(5)
	v_mfma_f32_16x16x32_bf16 v[2:5], v[22:25], v[34:37], v[2:5]
	global_load_dwordx4 v[22:25], v[52:53], off offset:256
	s_waitcnt vmcnt(5)
	v_mfma_f32_16x16x32_bf16 v[2:5], v[30:33], v[38:41], v[2:5]
	global_load_dwordx4 v[30:33], v[52:53], off offset:272
	global_load_dwordx4 v[34:37], v[50:51], off offset:288
	global_load_dwordx4 v[38:41], v[50:51], off offset:304
	s_waitcnt vmcnt(6)
	v_mfma_f32_16x16x32_bf16 v[2:5], v[42:45], v[46:49], v[2:5]
	s_waitcnt vmcnt(3)
	v_mfma_f32_16x16x32_bf16 v[2:5], v[18:21], v[22:25], v[2:5]
	global_load_dwordx4 v[18:21], v[52:53], off offset:288
	global_load_dwordx4 v[22:25], v[52:53], off offset:304
	s_waitcnt vmcnt(4)
	v_mfma_f32_16x16x32_bf16 v[2:5], v[26:29], v[30:33], v[2:5]
	s_waitcnt vmcnt(1)
	v_mfma_f32_16x16x32_bf16 v[2:5], v[34:37], v[18:21], v[2:5]
	s_waitcnt vmcnt(0)
	v_mfma_f32_16x16x32_bf16 v[2:5], v[38:41], v[22:25], v[2:5]
	s_cbranch_scc1 .LBB0_2082

.Lthin_p53_t:
	s_cmp_ge_i32 s7, s26
	s_cbranch_scc1 .LBB0_2088
.LBB0_2087:
	s_ashr_i32 s25, s24, 31
	s_lshl_b64 s[40:41], s[24:25], 1
	v_lshl_add_u64 v[50:51], v[6:7], 0, s[40:41]
	v_lshl_add_u64 v[52:53], v[12:13], 0, s[40:41]
	global_load_dwordx4 v[18:21], v[50:51], off
	global_load_dwordx4 v[22:25], v[50:51], off offset:16
	global_load_dwordx4 v[26:29], v[52:53], off
	global_load_dwordx4 v[30:33], v[50:51], off offset:32
	global_load_dwordx4 v[34:37], v[52:53], off offset:16
	global_load_dwordx4 v[38:41], v[52:53], off offset:32
	global_load_dwordx4 v[42:45], v[50:51], off offset:48
	global_load_dwordx4 v[46:49], v[52:53], off offset:48
	s_add_i32 s7, s7, 2
	s_addk_i32 s24, 0x100
	s_cmp_lt_i32 s7, s26
	s_waitcnt vmcnt(5)
	v_mfma_f32_16x16x32_bf16 v[2:5], v[18:21], v[26:29], v[2:5]
	global_load_dwordx4 v[18:21], v[50:51], off offset:256
	global_load_dwordx4 v[26:29], v[50:51], off offset:272
	s_waitcnt vmcnt(5)
	v_mfma_f32_16x16x32_bf16 v[2:5], v[22:25], v[34:37], v[2:5]
	global_load_dwordx4 v[22:25], v[52:53], off offset:256
	s_waitcnt vmcnt(5)
	v_mfma_f32_16x16x32_bf16 v[2:5], v[30:33], v[38:41], v[2:5]
	global_load_dwordx4 v[30:33], v[52:53], off offset:272
	global_load_dwordx4 v[34:37], v[50:51], off offset:288
	global_load_dwordx4 v[38:41], v[50:51], off offset:304
	s_waitcnt vmcnt(6)
	v_mfma_f32_16x16x32_bf16 v[2:5], v[42:45], v[46:49], v[2:5]
	s_waitcnt vmcnt(3)
	v_mfma_f32_16x16x32_bf16 v[2:5], v[18:21], v[22:25], v[2:5]
	global_load_dwordx4 v[18:21], v[52:53], off offset:288
	global_load_dwordx4 v[22:25], v[52:53], off offset:304
	s_waitcnt vmcnt(4)
	v_mfma_f32_16x16x32_bf16 v[2:5], v[26:29], v[30:33], v[2:5]
	s_waitcnt vmcnt(1)
	v_mfma_f32_16x16x32_bf16 v[2:5], v[34:37], v[18:21], v[2:5]
	s_waitcnt vmcnt(0)
	v_mfma_f32_16x16x32_bf16 v[2:5], v[38:41], v[22:25], v[2:5]
	s_cbranch_scc1 .LBB0_2087
